# v28 plus tile-loop exit test moved onto the back edge (one taken branch per tile instead of two)
# speedup vs baseline: 1.0028x; 1.0028x over previous
; __device__ __forceinline__ void attn_unit(const Params& P, int li, LAS unsigned char* lds, int b, int h, int qb, float lam, float one_m_li) {
;     ...
;     int iend = NT, i = 0;
; #pragma unroll 1
;     for (; i < iend; ++i) {
;         const int t = NT - 1 - i;
;         if (t >= 1) asm volatile("s_waitcnt vmcnt(4) lgkmcnt(0)" ::: "memory"); else asm volatile("s_waitcnt vmcnt(0) lgkmcnt(0)" ::: "memory");
;         __builtin_amdgcn_s_barrier();
;         asm volatile("" ::: "memory");
;         if (i == 2) { const int tstop = (int)ctl[0]; const int ie = NT - (tstop < NT - 2 ? tstop : NT - 2); iend = ie; if (i >= ie) break; }
.LBB0_428:
	s_add_i32 s21, s21, 1
	v_cmp_ge_i32_e64 s[22:23], s21, v231
	s_nop 0
	s_andn2_b64 vcc, exec, s[22:23]
	s_cbranch_vccnz .LBB0_404
	s_branch .LBB0_438
